# v111 plus three small validated edits stacked: late queue-index prefetch for the forgetting-attention items, first K/V tile loads issued with the Q loads in that item's prologue, mlp-in K-loop head 8-
# speedup vs baseline: 1.0002x; 1.0002x over previous
; template <bool DRY>
; DI void run_phase(const CP& p, int ph, int l, char* smem) {
;     ...
;     case PH_M2:
;       for (int it = b0; it < 64; it += nb) ssm_carry_item(p, l, it, smem);
;       break;
;     case PH_M3:
;       FOR_QUEUE(it, 1024, p.wq + l * 2 + 1 + (DRY ? 32 : 0)) {
.LBB0_317:
	s_andn2_b64 vcc, exec, s[4:5]
	s_cbranch_vccnz .LBB0_661
	s_cmp_lt_i32 s87, 3
	s_mov_b64 s[4:5], -1
	s_cbranch_scc1 .LBB0_471
	s_cmp_lt_i32 s87, 4
	s_cbranch_scc1 .LBB0_390
	s_cmp_gt_i32 s87, 4
	s_cbranch_scc0 .LBB0_193
	s_mov_b32 s99, 8
	s_branch .LBB0_381

.LBB0_325:
	v_mov_b32_e32 v0, v202
	s_barrier
	s_nop 0
	v_cmp_eq_u32_e32 vcc, 0, v0
	s_and_saveexec_b64 s[4:5], vcc
	s_cbranch_execz .LBB0_329
	s_mov_b64 s[10:11], exec
	v_mbcnt_lo_u32_b32 v0, s10, 0
	v_mbcnt_hi_u32_b32 v0, s11, v0
	v_cmp_eq_u32_e32 vcc, 0, v0
	s_and_saveexec_b64 s[6:7], vcc
	s_cbranch_execz .LBB0_328
	s_bitcmp1_b32 s99, 2
	s_cbranch_scc0 .Lq3_fetch
	s_bitset0_b32 s99, 2
	s_waitcnt vmcnt(0)
	v_mov_b32_e32 v1, v248
	s_branch .LBB0_328
.Lq3_fetch:
	s_bcnt1_i32_b64 s8, s[10:11]
	v_mov_b32_e32 v1, s8
	global_atomic_add v1, v33, v1, s[14:15] offset:4 sc0

; template <bool DRY>
; DI void run_phase(const CP& p, int ph, int l, char* smem) {
;     ...
;       FOR_QUEUE(it, 1024, p.wq + l * 2 + 1 + (DRY ? 32 : 0)) {
;         if (DRY && !((it < 512) ? PROBE_SEL == 5 : PROBE_SEL == 6)) continue;
;         if (it < 512) {
;           const int qt = 63 - (it >> 3), bh = it & 7;
;           attn_item<2>(p, l, bh >> 2, bh & 3, qt, smem);
;         } else {
;           ssm_out_item(p, l, it - 512, smem);
.LBB0_329:
	s_or_b64 exec, exec, s[4:5]
	v_mov_b32_e32 v0, s41
	s_waitcnt lgkmcnt(0)
	s_barrier
	ds_read_b32 v0, v0
	s_movk_i32 s4, 0x3ff
	s_waitcnt lgkmcnt(0)
	v_cmp_lt_i32_e32 vcc, s4, v0
	v_readfirstlane_b32 s74, v0
	s_mov_b64 s[4:5], -1
	s_cbranch_vccnz .LBB0_324
	s_cmpk_gt_i32 s74, 0x1ff
	s_cbranch_scc0 .LBB0_344
	s_bitcmp1_b32 s99, 0
	s_cbranch_scc1 .Lcin_ready

; template <bool DRY>
; DI void run_phase(const CP& p, int ph, int l, char* smem) {
;     ...
;           ssm_out_item(p, l, it - 512, smem);
.Lcin_set:
	s_bitset1_b32 s99, 0

; DI float bflo(unsigned u) { return __uint_as_float(u << 16); }
; DI float bfhi(unsigned u) { return __uint_as_float(u & 0xffff0000u); }
; DI float shx32(float v) { return shx(v, get_tid() & 63, 32); }
; template <int MODE>
; DI void attn_item(const CP& p, int l, int b, int head, int qt, char* smem) {
;     ...
;   const int q0 = qt * 256, qw0 = q0 + w * 32, qrow = qw0 + l32;
;   bf16x8 qf[4];
; #pragma unroll
;   for (int ks = 0; ks < 4; ++ks) qf[ks] = *(const bf16x8*)(TMb + (size_t)qrow * TMW + qoff + ks * 16 + hh * 8);
;   if (MODE == 1) {
;     if (tid < 384) sBias[tid] = (tid >= 128 && tid < 256) ? p.rel_bias[p.bucket[tid - 128] * 4 + head] * LOG2E : -INFINITY;
;   }
;   const int kt_hi = 4 * qt + 3;
;   const int kt_lo = (MODE == 1) ? (4 * qt - 2 > 0 ? 4 * qt - 2 : 0) : 0;
;   f32x16 o[2];
; #pragma unroll
;   for (int r = 0; r < 16; ++r) { o[0][r] = 0.f; o[1][r] = 0.f; }
;   float m = -INFINITY, lsum = 0.f, run = 1.f, Fq2 = 0.f;
;   bool first = true;
;   if (MODE == 2) m = 0.f;
;   if (MODE == 1) { m = p.sinks[l * 4 + head] * LOG2E; lsum = 1.f; }
;   float qbound2 = 0.f;
;   if (MODE == 2) {
;     Fq2 = Fb[qrow] * LOG2E;
;     float qn = 0.f;
; #pragma unroll
;     for (int ks = 0; ks < 4; ++ks) {
;       const u32x4 qq = __builtin_bit_cast(u32x4, qf[ks]);
;       qn += bflo(qq.x) * bflo(qq.x) + bfhi(qq.x) * bfhi(qq.x) + bflo(qq.y) * bflo(qq.y) + bfhi(qq.y) * bfhi(qq.y);
;       qn += bflo(qq.z) * bflo(qq.z) + bfhi(qq.z) * bfhi(qq.z) + bflo(qq.w) * bflo(qq.w) + bfhi(qq.w) * bfhi(qq.w);
;     }
;     qn += shx32(qn);
;     const float km2 = __uint_as_float(p.kmax[b * 4 + head]);
;     qbound2 = sqrtf(qn * km2) * 1.002f + 1e-3f;
;   }
;   u32x4 rk[1], rv[1];
;   float rf = 0.f;
.LBB0_347:
	s_or_b64 exec, exec, s[4:5]
	s_and_b32 s38, s74, 3
	s_ashr_i32 s75, s74, 3
	s_bfe_u32 s39, s74, 0x10002
	s_lshl_b32 s76, s38, 6
	s_sub_i32 s6, 63, s75
	s_add_i32 s7, s76, 0x180
	s_mul_i32 s4, s39, 0x3400000
	s_add_u32 s10, s18, s4
	s_addc_u32 s11, s19, 0
	s_mul_i32 s4, s39, 0x1400000
	s_add_u32 s4, s65, s4
	s_addc_u32 s5, s90, 0
	s_lshl_b32 s8, s39, 18
	s_add_u32 s8, s24, s8
	s_addc_u32 s9, s25, 0
	s_lshl_b32 s48, s38, 16
	s_add_u32 s70, s8, s48
	v_ashrrev_i32_e32 v0, 1, v181
	s_addc_u32 s71, s9, 0
	s_lshl_b32 s6, s6, 8
	v_and_b32_e32 v0, 0xffffffe0, v0
	v_and_b32_e32 v2, 31, v181
	v_add_u32_e32 v183, s6, v0
	v_or_b32_e32 v168, v183, v2
	v_mov_b64_e32 v[0:1], s[10:11]
	v_bfe_u32 v180, v181, 5, 1
	v_mad_i64_i32 v[4:5], s[72:73], v168, s45, v[0:1]
	s_lshl_b32 s48, s38, 7
	v_lshl_add_u64 v[4:5], v[4:5], 0, s[48:49]
	v_lshlrev_b32_e32 v32, 4, v180
	v_lshl_add_u64 v[4:5], v[4:5], 0, v[32:33]
	global_load_dwordx4 v[130:133], v[4:5], off offset:1792
	global_load_dwordx4 v[134:137], v[4:5], off offset:1824
	global_load_dwordx4 v[138:141], v[4:5], off offset:1856
	global_load_dwordx4 v[142:145], v[4:5], off offset:1888
	v_ashrrev_i32_e32 v169, 31, v168
	v_lshl_add_u64 v[4:5], v[168:169], 2, s[70:71]
	global_load_dword v3, v[4:5], off
	s_or_b32 s6, s6, 0xc0
	v_ashrrev_i32_e32 v169, 3, v181
	v_add_u32_e32 v7, s6, v169
	v_mad_i64_i32 v[0:1], s[72:73], v7, s45, v[0:1]
	v_lshlrev_b32_e32 v7, 3, v181
	v_and_b32_e32 v7, 56, v7
	v_lshl_add_u64 v[0:1], v[0:1], 0, s[48:49]
	v_lshlrev_b32_e32 v32, 1, v7
	v_lshl_add_u64 v[0:1], v[0:1], 0, v[32:33]
	s_and_b32 s8, s74, 7
	s_lshl_b32 s8, s8, 2
	v_mov_b32_e32 v184, 0
	global_load_dwordx4 v[146:149], v[0:1], off offset:2304
	v_add_u32_e32 v0, s7, v169
	v_ashrrev_i32_e32 v1, 31, v0
	v_lshlrev_b64 v[0:1], 15, v[0:1]
	v_lshl_add_u64 v[0:1], s[4:5], 0, v[0:1]
	s_mov_b32 s7, s49
	v_lshl_add_u64 v[8:9], s[6:7], 1, v[0:1]
	v_lshl_add_u64 v[8:9], v[8:9], 0, v[32:33]
	global_load_dwordx4 v[150:153], v[8:9], off
	s_waitcnt vmcnt(0)
	v_and_b32_e32 v5, 0xffff0000, v130
	v_lshlrev_b32_e32 v4, 16, v130
	v_mul_f32_e32 v5, v5, v5
	v_fmac_f32_e32 v5, v4, v4
	v_lshlrev_b32_e32 v4, 16, v131
	v_fmac_f32_e32 v5, v4, v4
	v_and_b32_e32 v4, 0xffff0000, v131
	v_and_b32_e32 v6, 0xffff0000, v132
	v_fmac_f32_e32 v5, v4, v4
	v_lshlrev_b32_e32 v4, 16, v132
	v_mul_f32_e32 v6, v6, v6
	v_fmac_f32_e32 v6, v4, v4
	v_lshlrev_b32_e32 v4, 16, v133
	v_fmac_f32_e32 v6, v4, v4
	v_and_b32_e32 v4, 0xffff0000, v133
	v_fmac_f32_e32 v6, v4, v4
	v_add_f32_e32 v4, v6, v5
	v_and_b32_e32 v6, 0xffff0000, v134
	v_lshlrev_b32_e32 v5, 16, v134
	v_mul_f32_e32 v6, v6, v6
	v_fmac_f32_e32 v6, v5, v5
	v_lshlrev_b32_e32 v5, 16, v135
	v_fmac_f32_e32 v6, v5, v5
	v_and_b32_e32 v5, 0xffff0000, v135
	v_fmac_f32_e32 v6, v5, v5
	v_add_f32_e32 v4, v4, v6
	v_and_b32_e32 v6, 0xffff0000, v136
	v_lshlrev_b32_e32 v5, 16, v136
	v_mul_f32_e32 v6, v6, v6
	v_fmac_f32_e32 v6, v5, v5
	v_lshlrev_b32_e32 v5, 16, v137
	v_fmac_f32_e32 v6, v5, v5
	v_and_b32_e32 v5, 0xffff0000, v137
	v_fmac_f32_e32 v6, v5, v5
	v_add_f32_e32 v4, v6, v4
	v_and_b32_e32 v6, 0xffff0000, v138
	v_lshlrev_b32_e32 v5, 16, v138
	v_mul_f32_e32 v6, v6, v6
	v_fmac_f32_e32 v6, v5, v5
	v_lshlrev_b32_e32 v5, 16, v139
	v_fmac_f32_e32 v6, v5, v5
	v_and_b32_e32 v5, 0xffff0000, v139
	v_fmac_f32_e32 v6, v5, v5
	v_add_f32_e32 v4, v6, v4
	v_and_b32_e32 v6, 0xffff0000, v140
	v_lshlrev_b32_e32 v5, 16, v140
	v_mul_f32_e32 v6, v6, v6
	v_fmac_f32_e32 v6, v5, v5
	v_lshlrev_b32_e32 v5, 16, v141
	v_fmac_f32_e32 v6, v5, v5
	v_and_b32_e32 v5, 0xffff0000, v141
	v_fmac_f32_e32 v6, v5, v5
	v_add_f32_e32 v4, v6, v4
	v_and_b32_e32 v6, 0xffff0000, v142
	v_lshlrev_b32_e32 v5, 16, v142
	v_mul_f32_e32 v6, v6, v6
	v_fmac_f32_e32 v6, v5, v5
	v_lshlrev_b32_e32 v5, 16, v143
	v_fmac_f32_e32 v6, v5, v5
	v_and_b32_e32 v5, 0xffff0000, v143
	v_fmac_f32_e32 v6, v5, v5
	v_add_f32_e32 v4, v6, v4
	v_and_b32_e32 v6, 0xffff0000, v144
	v_lshlrev_b32_e32 v5, 16, v144
	v_mul_f32_e32 v6, v6, v6
	v_fmac_f32_e32 v6, v5, v5
	v_lshlrev_b32_e32 v5, 16, v145
	v_fmac_f32_e32 v6, v5, v5
	v_and_b32_e32 v5, 0xffff0000, v145
	v_fmac_f32_e32 v6, v5, v5
	v_mov_b32_e32 v5, v202
	v_add_f32_e32 v4, v6, v4
	v_mov_b32_e32 v6, s8
	global_load_dword v6, v6, s[12:13]
	v_lshlrev_b32_e32 v5, 2, v5
	v_bitop3_b32 v5, v5, s84, v211 bitop3:0x6c
	ds_bpermute_b32 v5, v5, v4
	v_cmp_gt_i32_e64 s[4:5], 64, v181
	s_and_saveexec_b64 s[72:73], s[4:5]
	s_cbranch_execz .LBB0_349
	v_add_u32_e32 v8, s6, v181
	v_ashrrev_i32_e32 v9, 31, v8
	v_lshl_add_u64 v[8:9], v[8:9], 2, s[70:71]
	global_load_dword v7, v[8:9], off
	s_waitcnt vmcnt(0)
	v_mul_f32_e32 v184, 0x3fb8aa3b, v7

; template <int MODE>
; DI void attn_item(const CP& p, int l, int b, int head, int qt, char* smem) {
;     ...
;     const bool more = kt > kt_lo;
;     if (more) ATT_GL(kt - 1)
;     const int k0 = kt * 64;
;     if (k0 <= qw0 + 31 && !wdone && !(MODE == 1 && k0 + 63 < qw0 - 127)) {
;       const u16* cK = sK + buf * 4608;
;       const u16* cV = sV + buf * 4608;
;       const int kbase = k0 + 4 * hh;
;       f32x16 s[2];
;       if (MODE == 2) {
;         const bool need_mask = (k0 + 63 > qw0);
;         const float fqm = Fq2 - m;
;     ...
;         if (__builtin_amdgcn_readfirstlane((int)need_mask)) { FX_INIT(true) } else { FX_INIT(false) }
.LBB0_357:
	v_mov_b32_e32 v174, 0
	v_readfirstlane_b32 s8, v202
	s_cmp_lg_u32 s8, 0
	s_cbranch_scc1 .Lfx_nopf
	s_bitcmp1_b32 s99, 2
	s_cbranch_scc1 .Lfx_nopf
	s_bitset1_b32 s99, 2
	s_mov_b64 vcc, exec
	s_mov_b64 exec, 1
	v_mov_b32_e32 v248, 1
	global_atomic_add v248, v33, v248, s[14:15] offset:4 sc0
	s_mov_b64 exec, vcc
.Lfx_nopf:
.LBB0_358:
	v_cmp_le_i32_e32 vcc, v174, v189
	s_xor_b64 s[76:77], s[76:77], -1
	s_and_b64 s[78:79], vcc, s[76:77]
	s_and_saveexec_b64 s[76:77], s[78:79]
	s_cbranch_execz .LBB0_367
	s_mul_i32 s81, s92, 0x1200
	v_lshl_add_u32 v195, s81, 1, v191
	ds_read_b128 v[98:101], v195
	ds_read_b128 v[102:105], v195 offset:32
	ds_read_b128 v[106:109], v195 offset:64
	ds_read_b128 v[110:113], v195 offset:96
	v_or_b32_e32 v1, 63, v174
	v_cmp_gt_i32_e32 vcc, v1, v183
	v_sub_f32_e32 v0, v186, v177
	s_nop 0
	v_cndmask_b32_e64 v1, 0, 1, vcc
	s_nop 0
	v_readfirstlane_b32 s8, v1
	v_lshl_add_u32 v1, s92, 8, v190
	s_bitcmp1_b32 s8, 0
	s_cbranch_scc1 .Lfx_masked
	ds_read_b128 v[216:219], v1 offset:36864
	ds_read_b128 v[220:223], v1 offset:36896
	ds_read_b128 v[224:227], v1 offset:36928
	ds_read_b128 v[228:231], v1 offset:36960
	ds_read_b128 v[232:235], v1 offset:36992
	ds_read_b128 v[236:239], v1 offset:37024
	ds_read_b128 v[240:243], v1 offset:37056
	ds_read_b128 v[244:247], v1 offset:37088
	s_waitcnt lgkmcnt(4)
	v_sub_f32_e32 v66, v0, v216
	v_sub_f32_e32 v67, v0, v217
	v_sub_f32_e32 v68, v0, v218
	v_sub_f32_e32 v69, v0, v219
	v_sub_f32_e32 v70, v0, v220
	v_sub_f32_e32 v71, v0, v221
	v_sub_f32_e32 v72, v0, v222
	v_sub_f32_e32 v73, v0, v223
	v_sub_f32_e32 v74, v0, v224
	v_sub_f32_e32 v75, v0, v225
	v_sub_f32_e32 v76, v0, v226
	v_sub_f32_e32 v77, v0, v227
	v_sub_f32_e32 v78, v0, v228
	v_sub_f32_e32 v79, v0, v229
	v_sub_f32_e32 v80, v0, v230
	v_sub_f32_e32 v81, v0, v231
	ds_read_b128 v[114:117], v195 offset:4608
	ds_read_b128 v[118:121], v195 offset:4640
	ds_read_b128 v[122:125], v195 offset:4672
	ds_read_b128 v[126:129], v195 offset:4704
	s_waitcnt lgkmcnt(4)
	v_sub_f32_e32 v82, v0, v232
	v_sub_f32_e32 v83, v0, v233
	v_sub_f32_e32 v84, v0, v234
	v_sub_f32_e32 v85, v0, v235
	v_sub_f32_e32 v86, v0, v236
	v_sub_f32_e32 v87, v0, v237
	v_sub_f32_e32 v88, v0, v238
	v_sub_f32_e32 v89, v0, v239
	v_sub_f32_e32 v90, v0, v240
	v_sub_f32_e32 v91, v0, v241
	v_sub_f32_e32 v92, v0, v242
	v_sub_f32_e32 v93, v0, v243
	v_sub_f32_e32 v94, v0, v244
	v_sub_f32_e32 v95, v0, v245
	v_sub_f32_e32 v96, v0, v246
	v_sub_f32_e32 v97, v0, v247
	s_branch .Lfx_s

; template <bool DRY>
; DI void run_phase(const CP& p, int ph, int l, char* smem) {
;     ...
;       for (int it = b0; it < 64; it += nb) ssm_carry_item(p, l, it, smem);
;       break;
;     case PH_M3:
;       FOR_QUEUE(it, 1024, p.wq + l * 2 + 1 + (DRY ? 32 : 0)) {
.LBB0_389:
	s_cmp_eq_u32 s99, 8
	s_cbranch_scc1 .Lm3_entry
	s_mov_b64 s[4:5], 0
